# k=6: OpMerge<0,1,2> epilogues software-pipelined (gate and partial-sum loads of several row groups in flight)
# speedup vs baseline: 1.0040x; 1.0040x over previous
; __device__ __forceinline__ u32x4 pack8(f32x4 v0, f32x4 v1) { u32x4 o; o.x = pkbf(v0.x, v0.y); o.y = pkbf(v0.z, v0.w); o.z = pkbf(v1.x, v1.y); o.w = pkbf(v1.z, v1.w); return o; }
;     __device__ __forceinline__ void operator()(int row, int col, f32x4 v0, f32x4 v1) const { *(u32x4*)(G + (size_t)row * 1024 + col) = pack8(v0, v1); }
;     __device__ __forceinline__ void operator()(const pg8::f32x4 (&acc)[2][2][4][2], const pg8::Unit& u, int wr, int wc, int fr, int fq) const {
;         const int row0 = u.pm * 256 + wr * 64 + fr, col0 = u.pn * 256 + wc * 32 + 8 * fq;
; #pragma unroll
;         for (int ai = 0; ai < 2; ++ai)
; #pragma unroll
;             for (int m = 0; m < 4; ++m)
; #pragma unroll
;                 for (int bj = 0; bj < 2; ++bj) { op(row0 + ai * 128 + m * 16, col0 + bj * 128, acc[ai][bj][m][0], acc[ai][bj][m][1]); asm volatile("" ::: "memory"); }
;     }
;     __device__ __forceinline__ void operator()(int row, int col, f32x4 v0, f32x4 v1) const {
;         f32x4 g0, g1; unpack8(*(const u32x4*)(GT + (size_t)row * 3072 + KB * 1024 + col), g0, g1);
;         float* mf = MF + (size_t)row * 1024 + col;
;         f32x4 r0 = g0 * v0, r1 = g1 * v1;
;         if (KB > 0) { r0 += *(const f32x4*)mf; r1 += *(const f32x4*)(mf + 4); }
;         if (KB < 2) { *(f32x4*)mf = r0; *(f32x4*)(mf + 4) = r1; }
;         else *(u32x4*)(MB + (size_t)row * 1024 + col) = pack8(r0, r1);
;     }
.LBB0_180:
	v_mul_u32_u24_e32 v165, 0x1800, v161
	v_lshl_add_u32 v165, v163, 1, v165
	v_lshlrev_b32_e32 v170, 12, v161
	v_lshl_add_u32 v170, v163, 2, v170
	s_mul_i32 vcc_lo, s95, 0x180000
	s_lshl_b32 vcc_hi, s94, 9
	s_add_u32 vcc_lo, vcc_lo, vcc_hi
	s_add_u32 s4, s48, vcc_lo
	s_addc_u32 s5, s49, 0
	s_lshl_b32 vcc_lo, s95, 20
	s_lshl_b32 vcc_hi, s94, 10
	s_add_u32 vcc_lo, vcc_lo, vcc_hi
	s_add_u32 s6, s50, vcc_lo
	s_addc_u32 s7, s51, 0
	s_mov_b64 s[98:99], s[6:7]
	global_load_dwordx4 v[198:201], v165, s[4:5]
	global_load_dwordx4 v[202:205], v165, s[4:5] offset:256
	s_add_u32 s4, s4, 0x18000
	s_addc_u32 s5, s5, 0
	global_load_dwordx4 v[206:209], v165, s[4:5]
	global_load_dwordx4 v[210:213], v165, s[4:5] offset:256
	s_add_u32 s4, s4, 0x18000
	s_addc_u32 s5, s5, 0
	global_load_dwordx4 v[214:217], v165, s[4:5]
	global_load_dwordx4 v[218:221], v165, s[4:5] offset:256
	s_add_u32 s4, s4, 0x18000
	s_addc_u32 s5, s5, 0
	global_load_dwordx4 v[222:225], v165, s[4:5]
	global_load_dwordx4 v[226:229], v165, s[4:5] offset:256
	s_add_u32 s4, s4, 0x78000
	s_addc_u32 s5, s5, 0
	global_load_dwordx4 v[230:233], v165, s[4:5]
	global_load_dwordx4 v[234:237], v165, s[4:5] offset:256
	s_add_u32 s4, s4, 0x18000
	s_addc_u32 s5, s5, 0
	global_load_dwordx4 v[238:241], v165, s[4:5]
	global_load_dwordx4 v[242:245], v165, s[4:5] offset:256
	s_waitcnt vmcnt(11)
	v_lshlrev_b32_e32 v140, 16, v198
	v_and_b32_e32 v141, 0xffff0000, v198
	v_lshlrev_b32_e32 v142, 16, v199
	v_and_b32_e32 v143, 0xffff0000, v199
	v_lshlrev_b32_e32 v144, 16, v200
	v_and_b32_e32 v145, 0xffff0000, v200
	v_lshlrev_b32_e32 v146, 16, v201
	v_and_b32_e32 v147, 0xffff0000, v201
	v_pk_mul_f32 v[126:127], v[126:127], v[140:141]
	v_pk_mul_f32 v[128:129], v[128:129], v[142:143]
	v_pk_mul_f32 v[122:123], v[122:123], v[144:145]
	v_pk_mul_f32 v[124:125], v[124:125], v[146:147]
	global_store_dwordx4 v170, v[126:129], s[98:99]
	global_store_dwordx4 v170, v[122:125], s[98:99] offset:16
	s_add_u32 s4, s4, 0x18000
	s_addc_u32 s5, s5, 0
	global_load_dwordx4 v[198:201], v165, s[4:5]
	s_waitcnt vmcnt(13)
	v_lshlrev_b32_e32 v140, 16, v202
	v_and_b32_e32 v141, 0xffff0000, v202
	v_lshlrev_b32_e32 v142, 16, v203
	v_and_b32_e32 v143, 0xffff0000, v203
	v_lshlrev_b32_e32 v144, 16, v204
	v_and_b32_e32 v145, 0xffff0000, v204
	v_lshlrev_b32_e32 v146, 16, v205
	v_and_b32_e32 v147, 0xffff0000, v205
	v_pk_mul_f32 v[118:119], v[118:119], v[140:141]
	v_pk_mul_f32 v[120:121], v[120:121], v[142:143]
	v_pk_mul_f32 v[114:115], v[114:115], v[144:145]
	v_pk_mul_f32 v[116:117], v[116:117], v[146:147]
	global_store_dwordx4 v170, v[118:121], s[98:99] offset:512
	global_store_dwordx4 v170, v[114:117], s[98:99] offset:528
	global_load_dwordx4 v[202:205], v165, s[4:5] offset:256
	s_waitcnt vmcnt(15)
	v_lshlrev_b32_e32 v140, 16, v206
	v_and_b32_e32 v141, 0xffff0000, v206
	v_lshlrev_b32_e32 v142, 16, v207
	v_and_b32_e32 v143, 0xffff0000, v207
	v_lshlrev_b32_e32 v144, 16, v208
	v_and_b32_e32 v145, 0xffff0000, v208
	v_lshlrev_b32_e32 v146, 16, v209
	v_and_b32_e32 v147, 0xffff0000, v209
	v_pk_mul_f32 v[110:111], v[110:111], v[140:141]
	v_pk_mul_f32 v[112:113], v[112:113], v[142:143]
	v_pk_mul_f32 v[106:107], v[106:107], v[144:145]
	v_pk_mul_f32 v[108:109], v[108:109], v[146:147]
	s_add_u32 s98, s98, 0x10000
	s_addc_u32 s99, s99, 0
	global_store_dwordx4 v170, v[110:113], s[98:99]
	global_store_dwordx4 v170, v[106:109], s[98:99] offset:16
	s_add_u32 s4, s4, 0x18000
	s_addc_u32 s5, s5, 0
	global_load_dwordx4 v[206:209], v165, s[4:5]
	s_waitcnt vmcnt(17)
	v_lshlrev_b32_e32 v140, 16, v210
	v_and_b32_e32 v141, 0xffff0000, v210
	v_lshlrev_b32_e32 v142, 16, v211
	v_and_b32_e32 v143, 0xffff0000, v211
	v_lshlrev_b32_e32 v144, 16, v212
	v_and_b32_e32 v145, 0xffff0000, v212
	v_lshlrev_b32_e32 v146, 16, v213
	v_and_b32_e32 v147, 0xffff0000, v213
	v_pk_mul_f32 v[102:103], v[102:103], v[140:141]
	v_pk_mul_f32 v[104:105], v[104:105], v[142:143]
	v_pk_mul_f32 v[98:99], v[98:99], v[144:145]
	v_pk_mul_f32 v[100:101], v[100:101], v[146:147]
	global_store_dwordx4 v170, v[102:105], s[98:99] offset:512
	global_store_dwordx4 v170, v[98:101], s[98:99] offset:528
	global_load_dwordx4 v[210:213], v165, s[4:5] offset:256
	s_waitcnt vmcnt(19)
	v_lshlrev_b32_e32 v140, 16, v214
	v_and_b32_e32 v141, 0xffff0000, v214
	v_lshlrev_b32_e32 v142, 16, v215
	v_and_b32_e32 v143, 0xffff0000, v215
	v_lshlrev_b32_e32 v144, 16, v216
	v_and_b32_e32 v145, 0xffff0000, v216
	v_lshlrev_b32_e32 v146, 16, v217
	v_and_b32_e32 v147, 0xffff0000, v217
	v_pk_mul_f32 v[94:95], v[94:95], v[140:141]
	v_pk_mul_f32 v[96:97], v[96:97], v[142:143]
	v_pk_mul_f32 v[90:91], v[90:91], v[144:145]
	v_pk_mul_f32 v[92:93], v[92:93], v[146:147]
	s_add_u32 s98, s98, 0x10000
	s_addc_u32 s99, s99, 0
	global_store_dwordx4 v170, v[94:97], s[98:99]
	global_store_dwordx4 v170, v[90:93], s[98:99] offset:16
	s_waitcnt vmcnt(20)
	v_lshlrev_b32_e32 v140, 16, v218
	v_and_b32_e32 v141, 0xffff0000, v218
	v_lshlrev_b32_e32 v142, 16, v219
	v_and_b32_e32 v143, 0xffff0000, v219
	v_lshlrev_b32_e32 v144, 16, v220
	v_and_b32_e32 v145, 0xffff0000, v220
	v_lshlrev_b32_e32 v146, 16, v221
	v_and_b32_e32 v147, 0xffff0000, v221
	v_pk_mul_f32 v[86:87], v[86:87], v[140:141]
	v_pk_mul_f32 v[88:89], v[88:89], v[142:143]
	v_pk_mul_f32 v[82:83], v[82:83], v[144:145]
	v_pk_mul_f32 v[84:85], v[84:85], v[146:147]
	global_store_dwordx4 v170, v[86:89], s[98:99] offset:512
	global_store_dwordx4 v170, v[82:85], s[98:99] offset:528
	s_waitcnt vmcnt(21)
; __device__ __forceinline__ u32x4 pack8(f32x4 v0, f32x4 v1) { u32x4 o; o.x = pkbf(v0.x, v0.y); o.y = pkbf(v0.z, v0.w); o.z = pkbf(v1.x, v1.y); o.w = pkbf(v1.z, v1.w); return o; }
;     __device__ __forceinline__ void operator()(int row, int col, f32x4 v0, f32x4 v1) const { *(u32x4*)(G + (size_t)row * 1024 + col) = pack8(v0, v1); }
;     __device__ __forceinline__ void operator()(const pg8::f32x4 (&acc)[2][2][4][2], const pg8::Unit& u, int wr, int wc, int fr, int fq) const {
;         const int row0 = u.pm * 256 + wr * 64 + fr, col0 = u.pn * 256 + wc * 32 + 8 * fq;
; #pragma unroll
;         for (int ai = 0; ai < 2; ++ai)
; #pragma unroll
;             for (int m = 0; m < 4; ++m)
; #pragma unroll
;                 for (int bj = 0; bj < 2; ++bj) { op(row0 + ai * 128 + m * 16, col0 + bj * 128, acc[ai][bj][m][0], acc[ai][bj][m][1]); asm volatile("" ::: "memory"); }
;     }
;     __device__ __forceinline__ void operator()(int row, int col, f32x4 v0, f32x4 v1) const {
;         f32x4 g0, g1; unpack8(*(const u32x4*)(GT + (size_t)row * 3072 + KB * 1024 + col), g0, g1);
;         float* mf = MF + (size_t)row * 1024 + col;
;         f32x4 r0 = g0 * v0, r1 = g1 * v1;
;         if (KB > 0) { r0 += *(const f32x4*)mf; r1 += *(const f32x4*)(mf + 4); }
;         if (KB < 2) { *(f32x4*)mf = r0; *(f32x4*)(mf + 4) = r1; }
;         else *(u32x4*)(MB + (size_t)row * 1024 + col) = pack8(r0, r1);
;     }
	v_lshlrev_b32_e32 v140, 16, v222
	v_and_b32_e32 v141, 0xffff0000, v222
	v_lshlrev_b32_e32 v142, 16, v223
	v_and_b32_e32 v143, 0xffff0000, v223
	v_lshlrev_b32_e32 v144, 16, v224
	v_and_b32_e32 v145, 0xffff0000, v224
	v_lshlrev_b32_e32 v146, 16, v225
	v_and_b32_e32 v147, 0xffff0000, v225
	v_pk_mul_f32 v[78:79], v[78:79], v[140:141]
	v_pk_mul_f32 v[80:81], v[80:81], v[142:143]
	v_pk_mul_f32 v[74:75], v[74:75], v[144:145]
	v_pk_mul_f32 v[76:77], v[76:77], v[146:147]
	s_add_u32 s98, s98, 0x10000
	s_addc_u32 s99, s99, 0
	global_store_dwordx4 v170, v[78:81], s[98:99]
	global_store_dwordx4 v170, v[74:77], s[98:99] offset:16
	s_waitcnt vmcnt(22)
	v_lshlrev_b32_e32 v140, 16, v226
	v_and_b32_e32 v141, 0xffff0000, v226
	v_lshlrev_b32_e32 v142, 16, v227
	v_and_b32_e32 v143, 0xffff0000, v227
	v_lshlrev_b32_e32 v144, 16, v228
	v_and_b32_e32 v145, 0xffff0000, v228
	v_lshlrev_b32_e32 v146, 16, v229
	v_and_b32_e32 v147, 0xffff0000, v229
	v_pk_mul_f32 v[70:71], v[70:71], v[140:141]
	v_pk_mul_f32 v[72:73], v[72:73], v[142:143]
	v_pk_mul_f32 v[66:67], v[66:67], v[144:145]
	v_pk_mul_f32 v[68:69], v[68:69], v[146:147]
	global_store_dwordx4 v170, v[70:73], s[98:99] offset:512
	global_store_dwordx4 v170, v[66:69], s[98:99] offset:528
	s_waitcnt vmcnt(23)
	v_lshlrev_b32_e32 v140, 16, v230
	v_and_b32_e32 v141, 0xffff0000, v230
	v_lshlrev_b32_e32 v142, 16, v231
	v_and_b32_e32 v143, 0xffff0000, v231
	v_lshlrev_b32_e32 v144, 16, v232
	v_and_b32_e32 v145, 0xffff0000, v232
	v_lshlrev_b32_e32 v146, 16, v233
	v_and_b32_e32 v147, 0xffff0000, v233
	v_pk_mul_f32 v[62:63], v[62:63], v[140:141]
	v_pk_mul_f32 v[64:65], v[64:65], v[142:143]
	v_pk_mul_f32 v[58:59], v[58:59], v[144:145]
	v_pk_mul_f32 v[60:61], v[60:61], v[146:147]
	s_add_u32 s98, s98, 0x50000
	s_addc_u32 s99, s99, 0
	global_store_dwordx4 v170, v[62:65], s[98:99]
	global_store_dwordx4 v170, v[58:61], s[98:99] offset:16
	s_waitcnt vmcnt(24)
	v_lshlrev_b32_e32 v140, 16, v234
	v_and_b32_e32 v141, 0xffff0000, v234
	v_lshlrev_b32_e32 v142, 16, v235
	v_and_b32_e32 v143, 0xffff0000, v235
	v_lshlrev_b32_e32 v144, 16, v236
	v_and_b32_e32 v145, 0xffff0000, v236
	v_lshlrev_b32_e32 v146, 16, v237
	v_and_b32_e32 v147, 0xffff0000, v237
	v_pk_mul_f32 v[54:55], v[54:55], v[140:141]
	v_pk_mul_f32 v[56:57], v[56:57], v[142:143]
	v_pk_mul_f32 v[50:51], v[50:51], v[144:145]
	v_pk_mul_f32 v[52:53], v[52:53], v[146:147]
	global_store_dwordx4 v170, v[54:57], s[98:99] offset:512
	global_store_dwordx4 v170, v[50:53], s[98:99] offset:528
	s_waitcnt vmcnt(25)
	v_lshlrev_b32_e32 v140, 16, v238
	v_and_b32_e32 v141, 0xffff0000, v238
	v_lshlrev_b32_e32 v142, 16, v239
	v_and_b32_e32 v143, 0xffff0000, v239
	v_lshlrev_b32_e32 v144, 16, v240
	v_and_b32_e32 v145, 0xffff0000, v240
	v_lshlrev_b32_e32 v146, 16, v241
	v_and_b32_e32 v147, 0xffff0000, v241
	v_pk_mul_f32 v[46:47], v[46:47], v[140:141]
	v_pk_mul_f32 v[48:49], v[48:49], v[142:143]
	v_pk_mul_f32 v[42:43], v[42:43], v[144:145]
	v_pk_mul_f32 v[44:45], v[44:45], v[146:147]
	s_add_u32 s98, s98, 0x10000
	s_addc_u32 s99, s99, 0
	global_store_dwordx4 v170, v[46:49], s[98:99]
	global_store_dwordx4 v170, v[42:45], s[98:99] offset:16
	s_waitcnt vmcnt(26)
	v_lshlrev_b32_e32 v140, 16, v242
	v_and_b32_e32 v141, 0xffff0000, v242
	v_lshlrev_b32_e32 v142, 16, v243
	v_and_b32_e32 v143, 0xffff0000, v243
	v_lshlrev_b32_e32 v144, 16, v244
	v_and_b32_e32 v145, 0xffff0000, v244
	v_lshlrev_b32_e32 v146, 16, v245
	v_and_b32_e32 v147, 0xffff0000, v245
	v_pk_mul_f32 v[38:39], v[38:39], v[140:141]
	v_pk_mul_f32 v[40:41], v[40:41], v[142:143]
	v_pk_mul_f32 v[34:35], v[34:35], v[144:145]
	v_pk_mul_f32 v[36:37], v[36:37], v[146:147]
	global_store_dwordx4 v170, v[38:41], s[98:99] offset:512
	global_store_dwordx4 v170, v[34:37], s[98:99] offset:528
	s_waitcnt vmcnt(25)
	v_lshlrev_b32_e32 v140, 16, v198
	v_and_b32_e32 v141, 0xffff0000, v198
	v_lshlrev_b32_e32 v142, 16, v199
	v_and_b32_e32 v143, 0xffff0000, v199
	v_lshlrev_b32_e32 v144, 16, v200
	v_and_b32_e32 v145, 0xffff0000, v200
	v_lshlrev_b32_e32 v146, 16, v201
	v_and_b32_e32 v147, 0xffff0000, v201
	v_pk_mul_f32 v[30:31], v[30:31], v[140:141]
	v_pk_mul_f32 v[32:33], v[32:33], v[142:143]
	v_pk_mul_f32 v[26:27], v[26:27], v[144:145]
	v_pk_mul_f32 v[28:29], v[28:29], v[146:147]
	s_add_u32 s98, s98, 0x10000
	s_addc_u32 s99, s99, 0
	global_store_dwordx4 v170, v[30:33], s[98:99]
	global_store_dwordx4 v170, v[26:29], s[98:99] offset:16
	s_waitcnt vmcnt(24)
	v_lshlrev_b32_e32 v140, 16, v202
	v_and_b32_e32 v141, 0xffff0000, v202
	v_lshlrev_b32_e32 v142, 16, v203
	v_and_b32_e32 v143, 0xffff0000, v203
	v_lshlrev_b32_e32 v144, 16, v204
	v_and_b32_e32 v145, 0xffff0000, v204
	v_lshlrev_b32_e32 v146, 16, v205
	v_and_b32_e32 v147, 0xffff0000, v205
	v_pk_mul_f32 v[22:23], v[22:23], v[140:141]
	v_pk_mul_f32 v[24:25], v[24:25], v[142:143]
	v_pk_mul_f32 v[18:19], v[18:19], v[144:145]
	v_pk_mul_f32 v[20:21], v[20:21], v[146:147]
	global_store_dwordx4 v170, v[22:25], s[98:99] offset:512
	global_store_dwordx4 v170, v[18:21], s[98:99] offset:528
	s_waitcnt vmcnt(23)
	v_lshlrev_b32_e32 v140, 16, v206
	v_and_b32_e32 v141, 0xffff0000, v206
	v_lshlrev_b32_e32 v142, 16, v207
	v_and_b32_e32 v143, 0xffff0000, v207
	v_lshlrev_b32_e32 v144, 16, v208
	v_and_b32_e32 v145, 0xffff0000, v208
	v_lshlrev_b32_e32 v146, 16, v209
	v_and_b32_e32 v147, 0xffff0000, v209
	v_pk_mul_f32 v[14:15], v[14:15], v[140:141]
	v_pk_mul_f32 v[16:17], v[16:17], v[142:143]
	v_pk_mul_f32 v[10:11], v[10:11], v[144:145]
	v_pk_mul_f32 v[12:13], v[12:13], v[146:147]
	s_add_u32 s98, s98, 0x10000
	s_addc_u32 s99, s99, 0
	global_store_dwordx4 v170, v[14:17], s[98:99]
	global_store_dwordx4 v170, v[10:13], s[98:99] offset:16
	s_waitcnt vmcnt(22)
	v_lshlrev_b32_e32 v140, 16, v210
	v_and_b32_e32 v141, 0xffff0000, v210
	v_lshlrev_b32_e32 v142, 16, v211
	v_and_b32_e32 v143, 0xffff0000, v211
	v_lshlrev_b32_e32 v144, 16, v212
	v_and_b32_e32 v145, 0xffff0000, v212
	v_lshlrev_b32_e32 v146, 16, v213
	v_and_b32_e32 v147, 0xffff0000, v213
	v_pk_mul_f32 v[6:7], v[6:7], v[140:141]
	v_pk_mul_f32 v[8:9], v[8:9], v[142:143]
	v_pk_mul_f32 v[2:3], v[2:3], v[144:145]
	v_pk_mul_f32 v[4:5], v[4:5], v[146:147]
	global_store_dwordx4 v170, v[6:9], s[98:99] offset:512
	global_store_dwordx4 v170, v[2:5], s[98:99] offset:528
	s_and_b64 vcc, exec, s[40:41]
	s_mov_b64 s[4:5], -1
	s_cbranch_vccnz .LBB0_168
	s_andn2_b64 vcc, exec, s[56:57]
	s_cbranch_vccnz .LBB0_167
	s_barrier
	s_branch .LBB0_167

; __device__ __forceinline__ u32x4 pack8(f32x4 v0, f32x4 v1) { u32x4 o; o.x = pkbf(v0.x, v0.y); o.y = pkbf(v0.z, v0.w); o.z = pkbf(v1.x, v1.y); o.w = pkbf(v1.z, v1.w); return o; }
;     __device__ __forceinline__ void operator()(int row, int col, f32x4 v0, f32x4 v1) const { *(u32x4*)(G + (size_t)row * 1024 + col) = pack8(v0, v1); }
;     __device__ __forceinline__ void operator()(const pg8::f32x4 (&acc)[2][2][4][2], const pg8::Unit& u, int wr, int wc, int fr, int fq) const {
;         const int row0 = u.pm * 256 + wr * 64 + fr, col0 = u.pn * 256 + wc * 32 + 8 * fq;
; #pragma unroll
;         for (int ai = 0; ai < 2; ++ai)
; #pragma unroll
;             for (int m = 0; m < 4; ++m)
; #pragma unroll
;                 for (int bj = 0; bj < 2; ++bj) { op(row0 + ai * 128 + m * 16, col0 + bj * 128, acc[ai][bj][m][0], acc[ai][bj][m][1]); asm volatile("" ::: "memory"); }
;     }
;     __device__ __forceinline__ void operator()(int row, int col, f32x4 v0, f32x4 v1) const {
;         f32x4 g0, g1; unpack8(*(const u32x4*)(GT + (size_t)row * 3072 + KB * 1024 + col), g0, g1);
;         float* mf = MF + (size_t)row * 1024 + col;
;         f32x4 r0 = g0 * v0, r1 = g1 * v1;
;         if (KB > 0) { r0 += *(const f32x4*)mf; r1 += *(const f32x4*)(mf + 4); }
;         if (KB < 2) { *(f32x4*)mf = r0; *(f32x4*)(mf + 4) = r1; }
;         else *(u32x4*)(MB + (size_t)row * 1024 + col) = pack8(r0, r1);
;     }
.LBB0_201:
	v_mul_u32_u24_e32 v165, 0x1800, v161
	v_lshl_add_u32 v165, v163, 1, v165
	v_lshlrev_b32_e32 v170, 12, v161
	v_lshl_add_u32 v170, v163, 2, v170
	s_mul_i32 vcc_lo, s78, 0x180000
	s_lshl_b32 vcc_hi, s76, 9
	s_add_u32 vcc_lo, vcc_lo, vcc_hi
	s_add_u32 vcc_lo, vcc_lo, 0x800
	s_add_u32 s4, s48, vcc_lo
	s_addc_u32 s5, s49, 0
	s_lshl_b32 vcc_lo, s78, 20
	s_lshl_b32 vcc_hi, s76, 10
	s_add_u32 vcc_lo, vcc_lo, vcc_hi
	s_add_u32 s6, s50, vcc_lo
	s_addc_u32 s7, s51, 0
	s_mov_b64 s[98:99], s[6:7]
	global_load_dwordx4 v[198:201], v165, s[4:5]
	global_load_dwordx4 v[202:205], v170, s[6:7]
	global_load_dwordx4 v[206:209], v170, s[6:7] offset:16
	global_load_dwordx4 v[210:213], v165, s[4:5] offset:256
	global_load_dwordx4 v[214:217], v170, s[6:7] offset:512
	global_load_dwordx4 v[218:221], v170, s[6:7] offset:528
	s_add_u32 s4, s4, 0x18000
	s_addc_u32 s5, s5, 0
	global_load_dwordx4 v[222:225], v165, s[4:5]
	s_add_u32 s6, s6, 0x10000
	s_addc_u32 s7, s7, 0
	global_load_dwordx4 v[226:229], v170, s[6:7]
	global_load_dwordx4 v[230:233], v170, s[6:7] offset:16
	global_load_dwordx4 v[234:237], v165, s[4:5] offset:256
	global_load_dwordx4 v[238:241], v170, s[6:7] offset:512
	global_load_dwordx4 v[242:245], v170, s[6:7] offset:528
	s_add_u32 s4, s4, 0x18000
	s_addc_u32 s5, s5, 0
	global_load_dwordx4 v[166:169], v165, s[4:5]
	s_add_u32 s6, s6, 0x10000
	s_addc_u32 s7, s7, 0
	global_load_dwordx4 v[174:177], v170, s[6:7]
	global_load_dwordx4 v[182:185], v170, s[6:7] offset:16
	s_waitcnt vmcnt(12)
	v_lshlrev_b32_e32 v140, 16, v198
	v_and_b32_e32 v141, 0xffff0000, v198
	v_lshlrev_b32_e32 v142, 16, v199
	v_and_b32_e32 v143, 0xffff0000, v199
	v_lshlrev_b32_e32 v144, 16, v200
	v_and_b32_e32 v145, 0xffff0000, v200
	v_lshlrev_b32_e32 v146, 16, v201
	v_and_b32_e32 v147, 0xffff0000, v201
	v_pk_fma_f32 v[126:127], v[126:127], v[140:141], v[202:203]
	v_pk_fma_f32 v[128:129], v[128:129], v[142:143], v[204:205]
	v_pk_fma_f32 v[122:123], v[122:123], v[144:145], v[206:207]
	v_pk_fma_f32 v[124:125], v[124:125], v[146:147], v[208:209]
	global_store_dwordx4 v170, v[126:129], s[98:99]
	global_store_dwordx4 v170, v[122:125], s[98:99] offset:16
	global_load_dwordx4 v[198:201], v165, s[4:5] offset:256
	global_load_dwordx4 v[202:205], v170, s[6:7] offset:512
	global_load_dwordx4 v[206:209], v170, s[6:7] offset:528
	s_waitcnt vmcnt(14)
	v_lshlrev_b32_e32 v140, 16, v210
	v_and_b32_e32 v141, 0xffff0000, v210
	v_lshlrev_b32_e32 v142, 16, v211
	v_and_b32_e32 v143, 0xffff0000, v211
	v_lshlrev_b32_e32 v144, 16, v212
	v_and_b32_e32 v145, 0xffff0000, v212
	v_lshlrev_b32_e32 v146, 16, v213
	v_and_b32_e32 v147, 0xffff0000, v213
	v_pk_fma_f32 v[118:119], v[118:119], v[140:141], v[214:215]
	v_pk_fma_f32 v[120:121], v[120:121], v[142:143], v[216:217]
	v_pk_fma_f32 v[114:115], v[114:115], v[144:145], v[218:219]
	v_pk_fma_f32 v[116:117], v[116:117], v[146:147], v[220:221]
	global_store_dwordx4 v170, v[118:121], s[98:99] offset:512
	global_store_dwordx4 v170, v[114:117], s[98:99] offset:528
	s_add_u32 s4, s4, 0x18000
	s_addc_u32 s5, s5, 0
	global_load_dwordx4 v[210:213], v165, s[4:5]
	s_add_u32 s6, s6, 0x10000
	s_addc_u32 s7, s7, 0
	global_load_dwordx4 v[214:217], v170, s[6:7]
	global_load_dwordx4 v[218:221], v170, s[6:7] offset:16
	s_waitcnt vmcnt(16)
	v_lshlrev_b32_e32 v140, 16, v222
	v_and_b32_e32 v141, 0xffff0000, v222
	v_lshlrev_b32_e32 v142, 16, v223
	v_and_b32_e32 v143, 0xffff0000, v223
	v_lshlrev_b32_e32 v144, 16, v224
	v_and_b32_e32 v145, 0xffff0000, v224
	v_lshlrev_b32_e32 v146, 16, v225
	v_and_b32_e32 v147, 0xffff0000, v225
	v_pk_fma_f32 v[110:111], v[110:111], v[140:141], v[226:227]
	v_pk_fma_f32 v[112:113], v[112:113], v[142:143], v[228:229]
	v_pk_fma_f32 v[106:107], v[106:107], v[144:145], v[230:231]
	v_pk_fma_f32 v[108:109], v[108:109], v[146:147], v[232:233]
	s_add_u32 s98, s98, 0x10000
	s_addc_u32 s99, s99, 0
	global_store_dwordx4 v170, v[110:113], s[98:99]
	global_store_dwordx4 v170, v[106:109], s[98:99] offset:16
	global_load_dwordx4 v[222:225], v165, s[4:5] offset:256
	global_load_dwordx4 v[226:229], v170, s[6:7] offset:512
	global_load_dwordx4 v[230:233], v170, s[6:7] offset:528
	s_waitcnt vmcnt(18)
	v_lshlrev_b32_e32 v140, 16, v234
	v_and_b32_e32 v141, 0xffff0000, v234
	v_lshlrev_b32_e32 v142, 16, v235
	v_and_b32_e32 v143, 0xffff0000, v235
	v_lshlrev_b32_e32 v144, 16, v236
	v_and_b32_e32 v145, 0xffff0000, v236
	v_lshlrev_b32_e32 v146, 16, v237
	v_and_b32_e32 v147, 0xffff0000, v237
	v_pk_fma_f32 v[102:103], v[102:103], v[140:141], v[238:239]
	v_pk_fma_f32 v[104:105], v[104:105], v[142:143], v[240:241]
	v_pk_fma_f32 v[98:99], v[98:99], v[144:145], v[242:243]
	v_pk_fma_f32 v[100:101], v[100:101], v[146:147], v[244:245]
	global_store_dwordx4 v170, v[102:105], s[98:99] offset:512
	global_store_dwordx4 v170, v[98:101], s[98:99] offset:528
	s_add_u32 s4, s4, 0x78000
	s_addc_u32 s5, s5, 0
	global_load_dwordx4 v[234:237], v165, s[4:5]
	s_add_u32 s6, s6, 0x50000
	s_addc_u32 s7, s7, 0
	global_load_dwordx4 v[238:241], v170, s[6:7]
	global_load_dwordx4 v[242:245], v170, s[6:7] offset:16
	s_waitcnt vmcnt(20)
	v_lshlrev_b32_e32 v140, 16, v166
	v_and_b32_e32 v141, 0xffff0000, v166
	v_lshlrev_b32_e32 v142, 16, v167
	v_and_b32_e32 v143, 0xffff0000, v167
	v_lshlrev_b32_e32 v144, 16, v168
	v_and_b32_e32 v145, 0xffff0000, v168
	v_lshlrev_b32_e32 v146, 16, v169
	v_and_b32_e32 v147, 0xffff0000, v169
	v_pk_fma_f32 v[94:95], v[94:95], v[140:141], v[174:175]
	v_pk_fma_f32 v[96:97], v[96:97], v[142:143], v[176:177]
	v_pk_fma_f32 v[90:91], v[90:91], v[144:145], v[182:183]
	v_pk_fma_f32 v[92:93], v[92:93], v[146:147], v[184:185]
	s_add_u32 s98, s98, 0x10000
	s_addc_u32 s99, s99, 0
	global_store_dwordx4 v170, v[94:97], s[98:99]
	global_store_dwordx4 v170, v[90:93], s[98:99] offset:16
	global_load_dwordx4 v[166:169], v165, s[4:5] offset:256
	global_load_dwordx4 v[174:177], v170, s[6:7] offset:512
	global_load_dwordx4 v[182:185], v170, s[6:7] offset:528
	s_waitcnt vmcnt(20)
; __device__ __forceinline__ u32x4 pack8(f32x4 v0, f32x4 v1) { u32x4 o; o.x = pkbf(v0.x, v0.y); o.y = pkbf(v0.z, v0.w); o.z = pkbf(v1.x, v1.y); o.w = pkbf(v1.z, v1.w); return o; }
;     __device__ __forceinline__ void operator()(int row, int col, f32x4 v0, f32x4 v1) const { *(u32x4*)(G + (size_t)row * 1024 + col) = pack8(v0, v1); }
;     __device__ __forceinline__ void operator()(const pg8::f32x4 (&acc)[2][2][4][2], const pg8::Unit& u, int wr, int wc, int fr, int fq) const {
;         const int row0 = u.pm * 256 + wr * 64 + fr, col0 = u.pn * 256 + wc * 32 + 8 * fq;
; #pragma unroll
;         for (int ai = 0; ai < 2; ++ai)
; #pragma unroll
;             for (int m = 0; m < 4; ++m)
; #pragma unroll
;                 for (int bj = 0; bj < 2; ++bj) { op(row0 + ai * 128 + m * 16, col0 + bj * 128, acc[ai][bj][m][0], acc[ai][bj][m][1]); asm volatile("" ::: "memory"); }
;     }
;     __device__ __forceinline__ void operator()(int row, int col, f32x4 v0, f32x4 v1) const {
;         f32x4 g0, g1; unpack8(*(const u32x4*)(GT + (size_t)row * 3072 + KB * 1024 + col), g0, g1);
;         float* mf = MF + (size_t)row * 1024 + col;
;         f32x4 r0 = g0 * v0, r1 = g1 * v1;
;         if (KB > 0) { r0 += *(const f32x4*)mf; r1 += *(const f32x4*)(mf + 4); }
;         if (KB < 2) { *(f32x4*)mf = r0; *(f32x4*)(mf + 4) = r1; }
;         else *(u32x4*)(MB + (size_t)row * 1024 + col) = pack8(r0, r1);
;     }
	v_lshlrev_b32_e32 v140, 16, v198
	v_and_b32_e32 v141, 0xffff0000, v198
	v_lshlrev_b32_e32 v142, 16, v199
	v_and_b32_e32 v143, 0xffff0000, v199
	v_lshlrev_b32_e32 v144, 16, v200
	v_and_b32_e32 v145, 0xffff0000, v200
	v_lshlrev_b32_e32 v146, 16, v201
	v_and_b32_e32 v147, 0xffff0000, v201
	v_pk_fma_f32 v[86:87], v[86:87], v[140:141], v[202:203]
	v_pk_fma_f32 v[88:89], v[88:89], v[142:143], v[204:205]
	v_pk_fma_f32 v[82:83], v[82:83], v[144:145], v[206:207]
	v_pk_fma_f32 v[84:85], v[84:85], v[146:147], v[208:209]
	global_store_dwordx4 v170, v[86:89], s[98:99] offset:512
	global_store_dwordx4 v170, v[82:85], s[98:99] offset:528
	s_add_u32 s4, s4, 0x18000
	s_addc_u32 s5, s5, 0
	global_load_dwordx4 v[198:201], v165, s[4:5]
	s_add_u32 s6, s6, 0x10000
	s_addc_u32 s7, s7, 0
	global_load_dwordx4 v[202:205], v170, s[6:7]
	global_load_dwordx4 v[206:209], v170, s[6:7] offset:16
	s_waitcnt vmcnt(20)
	v_lshlrev_b32_e32 v140, 16, v210
	v_and_b32_e32 v141, 0xffff0000, v210
	v_lshlrev_b32_e32 v142, 16, v211
	v_and_b32_e32 v143, 0xffff0000, v211
	v_lshlrev_b32_e32 v144, 16, v212
	v_and_b32_e32 v145, 0xffff0000, v212
	v_lshlrev_b32_e32 v146, 16, v213
	v_and_b32_e32 v147, 0xffff0000, v213
	v_pk_fma_f32 v[78:79], v[78:79], v[140:141], v[214:215]
	v_pk_fma_f32 v[80:81], v[80:81], v[142:143], v[216:217]
	v_pk_fma_f32 v[74:75], v[74:75], v[144:145], v[218:219]
	v_pk_fma_f32 v[76:77], v[76:77], v[146:147], v[220:221]
	s_add_u32 s98, s98, 0x10000
	s_addc_u32 s99, s99, 0
	global_store_dwordx4 v170, v[78:81], s[98:99]
	global_store_dwordx4 v170, v[74:77], s[98:99] offset:16
	global_load_dwordx4 v[210:213], v165, s[4:5] offset:256
	global_load_dwordx4 v[214:217], v170, s[6:7] offset:512
	global_load_dwordx4 v[218:221], v170, s[6:7] offset:528
	s_waitcnt vmcnt(20)
	v_lshlrev_b32_e32 v140, 16, v222
	v_and_b32_e32 v141, 0xffff0000, v222
	v_lshlrev_b32_e32 v142, 16, v223
	v_and_b32_e32 v143, 0xffff0000, v223
	v_lshlrev_b32_e32 v144, 16, v224
	v_and_b32_e32 v145, 0xffff0000, v224
	v_lshlrev_b32_e32 v146, 16, v225
	v_and_b32_e32 v147, 0xffff0000, v225
	v_pk_fma_f32 v[70:71], v[70:71], v[140:141], v[226:227]
	v_pk_fma_f32 v[72:73], v[72:73], v[142:143], v[228:229]
	v_pk_fma_f32 v[66:67], v[66:67], v[144:145], v[230:231]
	v_pk_fma_f32 v[68:69], v[68:69], v[146:147], v[232:233]
	global_store_dwordx4 v170, v[70:73], s[98:99] offset:512
	global_store_dwordx4 v170, v[66:69], s[98:99] offset:528
	s_add_u32 s4, s4, 0x18000
	s_addc_u32 s5, s5, 0
	global_load_dwordx4 v[222:225], v165, s[4:5]
	s_add_u32 s6, s6, 0x10000
	s_addc_u32 s7, s7, 0
	global_load_dwordx4 v[226:229], v170, s[6:7]
	global_load_dwordx4 v[230:233], v170, s[6:7] offset:16
	s_waitcnt vmcnt(20)
	v_lshlrev_b32_e32 v140, 16, v234
	v_and_b32_e32 v141, 0xffff0000, v234
	v_lshlrev_b32_e32 v142, 16, v235
	v_and_b32_e32 v143, 0xffff0000, v235
	v_lshlrev_b32_e32 v144, 16, v236
	v_and_b32_e32 v145, 0xffff0000, v236
	v_lshlrev_b32_e32 v146, 16, v237
	v_and_b32_e32 v147, 0xffff0000, v237
	v_pk_fma_f32 v[62:63], v[62:63], v[140:141], v[238:239]
	v_pk_fma_f32 v[64:65], v[64:65], v[142:143], v[240:241]
	v_pk_fma_f32 v[58:59], v[58:59], v[144:145], v[242:243]
	v_pk_fma_f32 v[60:61], v[60:61], v[146:147], v[244:245]
	s_add_u32 s98, s98, 0x50000
	s_addc_u32 s99, s99, 0
	global_store_dwordx4 v170, v[62:65], s[98:99]
	global_store_dwordx4 v170, v[58:61], s[98:99] offset:16
	global_load_dwordx4 v[234:237], v165, s[4:5] offset:256
	global_load_dwordx4 v[238:241], v170, s[6:7] offset:512
	global_load_dwordx4 v[242:245], v170, s[6:7] offset:528
	s_waitcnt vmcnt(20)
	v_lshlrev_b32_e32 v140, 16, v166
	v_and_b32_e32 v141, 0xffff0000, v166
	v_lshlrev_b32_e32 v142, 16, v167
	v_and_b32_e32 v143, 0xffff0000, v167
	v_lshlrev_b32_e32 v144, 16, v168
	v_and_b32_e32 v145, 0xffff0000, v168
	v_lshlrev_b32_e32 v146, 16, v169
	v_and_b32_e32 v147, 0xffff0000, v169
	v_pk_fma_f32 v[54:55], v[54:55], v[140:141], v[174:175]
	v_pk_fma_f32 v[56:57], v[56:57], v[142:143], v[176:177]
	v_pk_fma_f32 v[50:51], v[50:51], v[144:145], v[182:183]
	v_pk_fma_f32 v[52:53], v[52:53], v[146:147], v[184:185]
	global_store_dwordx4 v170, v[54:57], s[98:99] offset:512
	global_store_dwordx4 v170, v[50:53], s[98:99] offset:528
	s_add_u32 s4, s4, 0x18000
	s_addc_u32 s5, s5, 0
	global_load_dwordx4 v[166:169], v165, s[4:5]
	s_add_u32 s6, s6, 0x10000
	s_addc_u32 s7, s7, 0
	global_load_dwordx4 v[174:177], v170, s[6:7]
	global_load_dwordx4 v[182:185], v170, s[6:7] offset:16
	s_waitcnt vmcnt(20)
; __device__ __forceinline__ u32x4 pack8(f32x4 v0, f32x4 v1) { u32x4 o; o.x = pkbf(v0.x, v0.y); o.y = pkbf(v0.z, v0.w); o.z = pkbf(v1.x, v1.y); o.w = pkbf(v1.z, v1.w); return o; }
;     __device__ __forceinline__ void operator()(int row, int col, f32x4 v0, f32x4 v1) const { *(u32x4*)(G + (size_t)row * 1024 + col) = pack8(v0, v1); }
;     __device__ __forceinline__ void operator()(const pg8::f32x4 (&acc)[2][2][4][2], const pg8::Unit& u, int wr, int wc, int fr, int fq) const {
;         const int row0 = u.pm * 256 + wr * 64 + fr, col0 = u.pn * 256 + wc * 32 + 8 * fq;
; #pragma unroll
;         for (int ai = 0; ai < 2; ++ai)
; #pragma unroll
;             for (int m = 0; m < 4; ++m)
; #pragma unroll
;                 for (int bj = 0; bj < 2; ++bj) { op(row0 + ai * 128 + m * 16, col0 + bj * 128, acc[ai][bj][m][0], acc[ai][bj][m][1]); asm volatile("" ::: "memory"); }
;     }
;     __device__ __forceinline__ void operator()(int row, int col, f32x4 v0, f32x4 v1) const {
;         f32x4 g0, g1; unpack8(*(const u32x4*)(GT + (size_t)row * 3072 + KB * 1024 + col), g0, g1);
;         float* mf = MF + (size_t)row * 1024 + col;
;         f32x4 r0 = g0 * v0, r1 = g1 * v1;
;         if (KB > 0) { r0 += *(const f32x4*)mf; r1 += *(const f32x4*)(mf + 4); }
;         if (KB < 2) { *(f32x4*)mf = r0; *(f32x4*)(mf + 4) = r1; }
;         else *(u32x4*)(MB + (size_t)row * 1024 + col) = pack8(r0, r1);
;     }
	v_lshlrev_b32_e32 v140, 16, v198
	v_and_b32_e32 v141, 0xffff0000, v198
	v_lshlrev_b32_e32 v142, 16, v199
	v_and_b32_e32 v143, 0xffff0000, v199
	v_lshlrev_b32_e32 v144, 16, v200
	v_and_b32_e32 v145, 0xffff0000, v200
	v_lshlrev_b32_e32 v146, 16, v201
	v_and_b32_e32 v147, 0xffff0000, v201
	v_pk_fma_f32 v[46:47], v[46:47], v[140:141], v[202:203]
	v_pk_fma_f32 v[48:49], v[48:49], v[142:143], v[204:205]
	v_pk_fma_f32 v[42:43], v[42:43], v[144:145], v[206:207]
	v_pk_fma_f32 v[44:45], v[44:45], v[146:147], v[208:209]
	s_add_u32 s98, s98, 0x10000
	s_addc_u32 s99, s99, 0
	global_store_dwordx4 v170, v[46:49], s[98:99]
	global_store_dwordx4 v170, v[42:45], s[98:99] offset:16
	global_load_dwordx4 v[198:201], v165, s[4:5] offset:256
	global_load_dwordx4 v[202:205], v170, s[6:7] offset:512
	global_load_dwordx4 v[206:209], v170, s[6:7] offset:528
	s_waitcnt vmcnt(20)
	v_lshlrev_b32_e32 v140, 16, v210
	v_and_b32_e32 v141, 0xffff0000, v210
	v_lshlrev_b32_e32 v142, 16, v211
	v_and_b32_e32 v143, 0xffff0000, v211
	v_lshlrev_b32_e32 v144, 16, v212
	v_and_b32_e32 v145, 0xffff0000, v212
	v_lshlrev_b32_e32 v146, 16, v213
	v_and_b32_e32 v147, 0xffff0000, v213
	v_pk_fma_f32 v[38:39], v[38:39], v[140:141], v[214:215]
	v_pk_fma_f32 v[40:41], v[40:41], v[142:143], v[216:217]
	v_pk_fma_f32 v[34:35], v[34:35], v[144:145], v[218:219]
	v_pk_fma_f32 v[36:37], v[36:37], v[146:147], v[220:221]
	global_store_dwordx4 v170, v[38:41], s[98:99] offset:512
	global_store_dwordx4 v170, v[34:37], s[98:99] offset:528
	s_waitcnt vmcnt(17)
	v_lshlrev_b32_e32 v140, 16, v222
	v_and_b32_e32 v141, 0xffff0000, v222
	v_lshlrev_b32_e32 v142, 16, v223
	v_and_b32_e32 v143, 0xffff0000, v223
	v_lshlrev_b32_e32 v144, 16, v224
	v_and_b32_e32 v145, 0xffff0000, v224
	v_lshlrev_b32_e32 v146, 16, v225
	v_and_b32_e32 v147, 0xffff0000, v225
	v_pk_fma_f32 v[30:31], v[30:31], v[140:141], v[226:227]
	v_pk_fma_f32 v[32:33], v[32:33], v[142:143], v[228:229]
	v_pk_fma_f32 v[26:27], v[26:27], v[144:145], v[230:231]
	v_pk_fma_f32 v[28:29], v[28:29], v[146:147], v[232:233]
	s_add_u32 s98, s98, 0x10000
	s_addc_u32 s99, s99, 0
	global_store_dwordx4 v170, v[30:33], s[98:99]
	global_store_dwordx4 v170, v[26:29], s[98:99] offset:16
	s_waitcnt vmcnt(14)
	v_lshlrev_b32_e32 v140, 16, v234
	v_and_b32_e32 v141, 0xffff0000, v234
	v_lshlrev_b32_e32 v142, 16, v235
	v_and_b32_e32 v143, 0xffff0000, v235
	v_lshlrev_b32_e32 v144, 16, v236
	v_and_b32_e32 v145, 0xffff0000, v236
	v_lshlrev_b32_e32 v146, 16, v237
	v_and_b32_e32 v147, 0xffff0000, v237
	v_pk_fma_f32 v[22:23], v[22:23], v[140:141], v[238:239]
	v_pk_fma_f32 v[24:25], v[24:25], v[142:143], v[240:241]
	v_pk_fma_f32 v[18:19], v[18:19], v[144:145], v[242:243]
	v_pk_fma_f32 v[20:21], v[20:21], v[146:147], v[244:245]
	global_store_dwordx4 v170, v[22:25], s[98:99] offset:512
	global_store_dwordx4 v170, v[18:21], s[98:99] offset:528
	s_waitcnt vmcnt(11)
	v_lshlrev_b32_e32 v140, 16, v166
	v_and_b32_e32 v141, 0xffff0000, v166
	v_lshlrev_b32_e32 v142, 16, v167
	v_and_b32_e32 v143, 0xffff0000, v167
	v_lshlrev_b32_e32 v144, 16, v168
	v_and_b32_e32 v145, 0xffff0000, v168
	v_lshlrev_b32_e32 v146, 16, v169
	v_and_b32_e32 v147, 0xffff0000, v169
	v_pk_fma_f32 v[14:15], v[14:15], v[140:141], v[174:175]
	v_pk_fma_f32 v[16:17], v[16:17], v[142:143], v[176:177]
	v_pk_fma_f32 v[10:11], v[10:11], v[144:145], v[182:183]
	v_pk_fma_f32 v[12:13], v[12:13], v[146:147], v[184:185]
	s_add_u32 s98, s98, 0x10000
	s_addc_u32 s99, s99, 0
	global_store_dwordx4 v170, v[14:17], s[98:99]
	global_store_dwordx4 v170, v[10:13], s[98:99] offset:16
	s_waitcnt vmcnt(8)
	v_lshlrev_b32_e32 v140, 16, v198
	v_and_b32_e32 v141, 0xffff0000, v198
	v_lshlrev_b32_e32 v142, 16, v199
	v_and_b32_e32 v143, 0xffff0000, v199
	v_lshlrev_b32_e32 v144, 16, v200
	v_and_b32_e32 v145, 0xffff0000, v200
	v_lshlrev_b32_e32 v146, 16, v201
	v_and_b32_e32 v147, 0xffff0000, v201
	v_pk_fma_f32 v[6:7], v[6:7], v[140:141], v[202:203]
	v_pk_fma_f32 v[8:9], v[8:9], v[142:143], v[204:205]
	v_pk_fma_f32 v[2:3], v[2:3], v[144:145], v[206:207]
	v_pk_fma_f32 v[4:5], v[4:5], v[146:147], v[208:209]
	global_store_dwordx4 v170, v[6:9], s[98:99] offset:512
	global_store_dwordx4 v170, v[2:5], s[98:99] offset:528
	s_and_b64 vcc, exec, s[42:43]
	s_mov_b64 s[4:5], -1
	s_cbranch_vccnz .LBB0_189
	s_andn2_b64 vcc, exec, s[56:57]
	s_cbranch_vccnz .LBB0_188
	s_barrier
	s_branch .LBB0_188

; __device__ __forceinline__ u32x4 pack8(f32x4 v0, f32x4 v1) { u32x4 o; o.x = pkbf(v0.x, v0.y); o.y = pkbf(v0.z, v0.w); o.z = pkbf(v1.x, v1.y); o.w = pkbf(v1.z, v1.w); return o; }
;     __device__ __forceinline__ void operator()(int row, int col, f32x4 v0, f32x4 v1) const { *(u32x4*)(G + (size_t)row * 1024 + col) = pack8(v0, v1); }
;     __device__ __forceinline__ void operator()(const pg8::f32x4 (&acc)[2][2][4][2], const pg8::Unit& u, int wr, int wc, int fr, int fq) const {
;         const int row0 = u.pm * 256 + wr * 64 + fr, col0 = u.pn * 256 + wc * 32 + 8 * fq;
; #pragma unroll
;         for (int ai = 0; ai < 2; ++ai)
; #pragma unroll
;             for (int m = 0; m < 4; ++m)
; #pragma unroll
;                 for (int bj = 0; bj < 2; ++bj) { op(row0 + ai * 128 + m * 16, col0 + bj * 128, acc[ai][bj][m][0], acc[ai][bj][m][1]); asm volatile("" ::: "memory"); }
;     }
;     __device__ __forceinline__ void operator()(int row, int col, f32x4 v0, f32x4 v1) const {
;         f32x4 g0, g1; unpack8(*(const u32x4*)(GT + (size_t)row * 3072 + KB * 1024 + col), g0, g1);
;         float* mf = MF + (size_t)row * 1024 + col;
;         f32x4 r0 = g0 * v0, r1 = g1 * v1;
;         if (KB > 0) { r0 += *(const f32x4*)mf; r1 += *(const f32x4*)(mf + 4); }
;         if (KB < 2) { *(f32x4*)mf = r0; *(f32x4*)(mf + 4) = r1; }
;         else *(u32x4*)(MB + (size_t)row * 1024 + col) = pack8(r0, r1);
;     }
.LBB0_223:
	v_mul_u32_u24_e32 v234, 0x1800, v155
	v_lshl_add_u32 v234, v152, 1, v234
	v_lshlrev_b32_e32 v235, 12, v155
	v_lshl_add_u32 v235, v152, 2, v235
	v_lshlrev_b32_e32 v236, 11, v155
	v_lshl_add_u32 v236, v152, 1, v236
	s_mul_i32 vcc_lo, s78, 0x180000
	s_lshl_b32 vcc_hi, s76, 9
	s_add_u32 vcc_lo, vcc_lo, vcc_hi
	s_add_u32 vcc_lo, vcc_lo, 0x1000
	s_add_u32 s4, s48, vcc_lo
	s_addc_u32 s5, s49, 0
	s_lshl_b32 vcc_lo, s78, 20
	s_lshl_b32 vcc_hi, s76, 10
	s_add_u32 vcc_lo, vcc_lo, vcc_hi
	s_add_u32 s6, s50, vcc_lo
	s_addc_u32 s7, s51, 0
	s_lshl_b32 vcc_lo, s78, 19
	s_lshl_b32 vcc_hi, s76, 9
	s_add_u32 vcc_lo, vcc_lo, vcc_hi
	s_add_u32 s98, s88, vcc_lo
	s_addc_u32 s99, s89, 0
	global_load_dwordx4 v[156:159], v234, s[4:5]
	global_load_dwordx4 v[160:163], v235, s[6:7]
	global_load_dwordx4 v[164:167], v235, s[6:7] offset:16
	global_load_dwordx4 v[168:171], v234, s[4:5] offset:256
	global_load_dwordx4 v[174:177], v235, s[6:7] offset:512
	global_load_dwordx4 v[182:185], v235, s[6:7] offset:528
	s_add_u32 s4, s4, 0x18000
	s_addc_u32 s5, s5, 0
	global_load_dwordx4 v[198:201], v234, s[4:5]
	s_add_u32 s6, s6, 0x10000
	s_addc_u32 s7, s7, 0
	global_load_dwordx4 v[202:205], v235, s[6:7]
	global_load_dwordx4 v[206:209], v235, s[6:7] offset:16
	global_load_dwordx4 v[210:213], v234, s[4:5] offset:256
	global_load_dwordx4 v[214:217], v235, s[6:7] offset:512
	global_load_dwordx4 v[218:221], v235, s[6:7] offset:528
	s_add_u32 s4, s4, 0x18000
	s_addc_u32 s5, s5, 0
	global_load_dwordx4 v[222:225], v234, s[4:5]
	s_add_u32 s6, s6, 0x10000
	s_addc_u32 s7, s7, 0
	global_load_dwordx4 v[226:229], v235, s[6:7]
	global_load_dwordx4 v[230:233], v235, s[6:7] offset:16
	s_waitcnt vmcnt(12)
	v_lshlrev_b32_e32 v140, 16, v156
	v_and_b32_e32 v141, 0xffff0000, v156
	v_lshlrev_b32_e32 v142, 16, v157
	v_and_b32_e32 v143, 0xffff0000, v157
	v_lshlrev_b32_e32 v144, 16, v158
	v_and_b32_e32 v145, 0xffff0000, v158
	v_lshlrev_b32_e32 v146, 16, v159
	v_and_b32_e32 v147, 0xffff0000, v159
	v_pk_fma_f32 v[122:123], v[122:123], v[140:141], v[160:161]
	v_pk_fma_f32 v[124:125], v[124:125], v[142:143], v[162:163]
	v_pk_fma_f32 v[126:127], v[126:127], v[144:145], v[164:165]
	v_pk_fma_f32 v[128:129], v[128:129], v[146:147], v[166:167]
	v_cvt_pk_bf16_f32 v140, v122, v123
	v_cvt_pk_bf16_f32 v141, v124, v125
	v_cvt_pk_bf16_f32 v142, v126, v127
	v_cvt_pk_bf16_f32 v143, v128, v129
	global_store_dwordx4 v236, v[140:143], s[98:99]
	s_nop 1
	global_load_dwordx4 v[156:159], v234, s[4:5] offset:256
	global_load_dwordx4 v[160:163], v235, s[6:7] offset:512
	global_load_dwordx4 v[164:167], v235, s[6:7] offset:528
	s_waitcnt vmcnt(13)
	v_lshlrev_b32_e32 v140, 16, v168
	v_and_b32_e32 v141, 0xffff0000, v168
	v_lshlrev_b32_e32 v142, 16, v169
	v_and_b32_e32 v143, 0xffff0000, v169
	v_lshlrev_b32_e32 v144, 16, v170
	v_and_b32_e32 v145, 0xffff0000, v170
	v_lshlrev_b32_e32 v146, 16, v171
	v_and_b32_e32 v147, 0xffff0000, v171
	v_pk_fma_f32 v[118:119], v[118:119], v[140:141], v[174:175]
	v_pk_fma_f32 v[120:121], v[120:121], v[142:143], v[176:177]
	v_pk_fma_f32 v[114:115], v[114:115], v[144:145], v[182:183]
	v_pk_fma_f32 v[116:117], v[116:117], v[146:147], v[184:185]
	v_cvt_pk_bf16_f32 v140, v118, v119
	v_cvt_pk_bf16_f32 v141, v120, v121
	v_cvt_pk_bf16_f32 v142, v114, v115
	v_cvt_pk_bf16_f32 v143, v116, v117
	global_store_dwordx4 v236, v[140:143], s[98:99] offset:256
	s_nop 1
	s_add_u32 s4, s4, 0x18000
	s_addc_u32 s5, s5, 0
	global_load_dwordx4 v[168:171], v234, s[4:5]
	s_add_u32 s6, s6, 0x10000
	s_addc_u32 s7, s7, 0
	global_load_dwordx4 v[174:177], v235, s[6:7]
	global_load_dwordx4 v[182:185], v235, s[6:7] offset:16
	s_waitcnt vmcnt(14)
	v_lshlrev_b32_e32 v140, 16, v198
	v_and_b32_e32 v141, 0xffff0000, v198
	v_lshlrev_b32_e32 v142, 16, v199
	v_and_b32_e32 v143, 0xffff0000, v199
	v_lshlrev_b32_e32 v144, 16, v200
	v_and_b32_e32 v145, 0xffff0000, v200
	v_lshlrev_b32_e32 v146, 16, v201
	v_and_b32_e32 v147, 0xffff0000, v201
	v_pk_fma_f32 v[110:111], v[110:111], v[140:141], v[202:203]
	v_pk_fma_f32 v[112:113], v[112:113], v[142:143], v[204:205]
	v_pk_fma_f32 v[106:107], v[106:107], v[144:145], v[206:207]
	v_pk_fma_f32 v[108:109], v[108:109], v[146:147], v[208:209]
	v_cvt_pk_bf16_f32 v140, v110, v111
	v_cvt_pk_bf16_f32 v141, v112, v113
	v_cvt_pk_bf16_f32 v142, v106, v107
	v_cvt_pk_bf16_f32 v143, v108, v109
	s_add_u32 s98, s98, 0x8000
	s_addc_u32 s99, s99, 0
	global_store_dwordx4 v236, v[140:143], s[98:99]
	s_nop 1
	global_load_dwordx4 v[198:201], v234, s[4:5] offset:256
	global_load_dwordx4 v[202:205], v235, s[6:7] offset:512
	global_load_dwordx4 v[206:209], v235, s[6:7] offset:528
	s_waitcnt vmcnt(15)
	v_lshlrev_b32_e32 v140, 16, v210
	v_and_b32_e32 v141, 0xffff0000, v210
	v_lshlrev_b32_e32 v142, 16, v211
	v_and_b32_e32 v143, 0xffff0000, v211
	v_lshlrev_b32_e32 v144, 16, v212
	v_and_b32_e32 v145, 0xffff0000, v212
	v_lshlrev_b32_e32 v146, 16, v213
	v_and_b32_e32 v147, 0xffff0000, v213
	v_pk_fma_f32 v[102:103], v[102:103], v[140:141], v[214:215]
	v_pk_fma_f32 v[104:105], v[104:105], v[142:143], v[216:217]
	v_pk_fma_f32 v[98:99], v[98:99], v[144:145], v[218:219]
	v_pk_fma_f32 v[100:101], v[100:101], v[146:147], v[220:221]
	v_cvt_pk_bf16_f32 v140, v102, v103
	v_cvt_pk_bf16_f32 v141, v104, v105
	v_cvt_pk_bf16_f32 v142, v98, v99
	v_cvt_pk_bf16_f32 v143, v100, v101
	global_store_dwordx4 v236, v[140:143], s[98:99] offset:256
	s_nop 1
	s_add_u32 s4, s4, 0x78000
	s_addc_u32 s5, s5, 0
	global_load_dwordx4 v[210:213], v234, s[4:5]
	s_add_u32 s6, s6, 0x50000
	s_addc_u32 s7, s7, 0
	global_load_dwordx4 v[214:217], v235, s[6:7]
	global_load_dwordx4 v[218:221], v235, s[6:7] offset:16
	s_waitcnt vmcnt(16)
; __device__ __forceinline__ u32x4 pack8(f32x4 v0, f32x4 v1) { u32x4 o; o.x = pkbf(v0.x, v0.y); o.y = pkbf(v0.z, v0.w); o.z = pkbf(v1.x, v1.y); o.w = pkbf(v1.z, v1.w); return o; }
;     __device__ __forceinline__ void operator()(int row, int col, f32x4 v0, f32x4 v1) const { *(u32x4*)(G + (size_t)row * 1024 + col) = pack8(v0, v1); }
;     __device__ __forceinline__ void operator()(const pg8::f32x4 (&acc)[2][2][4][2], const pg8::Unit& u, int wr, int wc, int fr, int fq) const {
;         const int row0 = u.pm * 256 + wr * 64 + fr, col0 = u.pn * 256 + wc * 32 + 8 * fq;
; #pragma unroll
;         for (int ai = 0; ai < 2; ++ai)
; #pragma unroll
;             for (int m = 0; m < 4; ++m)
; #pragma unroll
;                 for (int bj = 0; bj < 2; ++bj) { op(row0 + ai * 128 + m * 16, col0 + bj * 128, acc[ai][bj][m][0], acc[ai][bj][m][1]); asm volatile("" ::: "memory"); }
;     }
;     __device__ __forceinline__ void operator()(int row, int col, f32x4 v0, f32x4 v1) const {
;         f32x4 g0, g1; unpack8(*(const u32x4*)(GT + (size_t)row * 3072 + KB * 1024 + col), g0, g1);
;         float* mf = MF + (size_t)row * 1024 + col;
;         f32x4 r0 = g0 * v0, r1 = g1 * v1;
;         if (KB > 0) { r0 += *(const f32x4*)mf; r1 += *(const f32x4*)(mf + 4); }
;         if (KB < 2) { *(f32x4*)mf = r0; *(f32x4*)(mf + 4) = r1; }
;         else *(u32x4*)(MB + (size_t)row * 1024 + col) = pack8(r0, r1);
;     }
	v_lshlrev_b32_e32 v140, 16, v222
	v_and_b32_e32 v141, 0xffff0000, v222
	v_lshlrev_b32_e32 v142, 16, v223
	v_and_b32_e32 v143, 0xffff0000, v223
	v_lshlrev_b32_e32 v144, 16, v224
	v_and_b32_e32 v145, 0xffff0000, v224
	v_lshlrev_b32_e32 v146, 16, v225
	v_and_b32_e32 v147, 0xffff0000, v225
	v_pk_fma_f32 v[94:95], v[94:95], v[140:141], v[226:227]
	v_pk_fma_f32 v[96:97], v[96:97], v[142:143], v[228:229]
	v_pk_fma_f32 v[90:91], v[90:91], v[144:145], v[230:231]
	v_pk_fma_f32 v[92:93], v[92:93], v[146:147], v[232:233]
	v_cvt_pk_bf16_f32 v140, v94, v95
	v_cvt_pk_bf16_f32 v141, v96, v97
	v_cvt_pk_bf16_f32 v142, v90, v91
	v_cvt_pk_bf16_f32 v143, v92, v93
	s_add_u32 s98, s98, 0x8000
	s_addc_u32 s99, s99, 0
	global_store_dwordx4 v236, v[140:143], s[98:99]
	s_nop 1
	global_load_dwordx4 v[222:225], v234, s[4:5] offset:256
	global_load_dwordx4 v[226:229], v235, s[6:7] offset:512
	global_load_dwordx4 v[230:233], v235, s[6:7] offset:528
	s_waitcnt vmcnt(16)
	v_lshlrev_b32_e32 v140, 16, v156
	v_and_b32_e32 v141, 0xffff0000, v156
	v_lshlrev_b32_e32 v142, 16, v157
	v_and_b32_e32 v143, 0xffff0000, v157
	v_lshlrev_b32_e32 v144, 16, v158
	v_and_b32_e32 v145, 0xffff0000, v158
	v_lshlrev_b32_e32 v146, 16, v159
	v_and_b32_e32 v147, 0xffff0000, v159
	v_pk_fma_f32 v[86:87], v[86:87], v[140:141], v[160:161]
	v_pk_fma_f32 v[88:89], v[88:89], v[142:143], v[162:163]
	v_pk_fma_f32 v[82:83], v[82:83], v[144:145], v[164:165]
	v_pk_fma_f32 v[84:85], v[84:85], v[146:147], v[166:167]
	v_cvt_pk_bf16_f32 v140, v86, v87
	v_cvt_pk_bf16_f32 v141, v88, v89
	v_cvt_pk_bf16_f32 v142, v82, v83
	v_cvt_pk_bf16_f32 v143, v84, v85
	global_store_dwordx4 v236, v[140:143], s[98:99] offset:256
	s_nop 1
	s_add_u32 s4, s4, 0x18000
	s_addc_u32 s5, s5, 0
	global_load_dwordx4 v[156:159], v234, s[4:5]
	s_add_u32 s6, s6, 0x10000
	s_addc_u32 s7, s7, 0
	global_load_dwordx4 v[160:163], v235, s[6:7]
	global_load_dwordx4 v[164:167], v235, s[6:7] offset:16
	s_waitcnt vmcnt(16)
	v_lshlrev_b32_e32 v140, 16, v168
	v_and_b32_e32 v141, 0xffff0000, v168
	v_lshlrev_b32_e32 v142, 16, v169
	v_and_b32_e32 v143, 0xffff0000, v169
	v_lshlrev_b32_e32 v144, 16, v170
	v_and_b32_e32 v145, 0xffff0000, v170
	v_lshlrev_b32_e32 v146, 16, v171
	v_and_b32_e32 v147, 0xffff0000, v171
	v_pk_fma_f32 v[78:79], v[78:79], v[140:141], v[174:175]
	v_pk_fma_f32 v[80:81], v[80:81], v[142:143], v[176:177]
	v_pk_fma_f32 v[74:75], v[74:75], v[144:145], v[182:183]
	v_pk_fma_f32 v[76:77], v[76:77], v[146:147], v[184:185]
	v_cvt_pk_bf16_f32 v140, v78, v79
	v_cvt_pk_bf16_f32 v141, v80, v81
	v_cvt_pk_bf16_f32 v142, v74, v75
	v_cvt_pk_bf16_f32 v143, v76, v77
	s_add_u32 s98, s98, 0x8000
	s_addc_u32 s99, s99, 0
	global_store_dwordx4 v236, v[140:143], s[98:99]
	s_nop 1
	global_load_dwordx4 v[168:171], v234, s[4:5] offset:256
	global_load_dwordx4 v[174:177], v235, s[6:7] offset:512
	global_load_dwordx4 v[182:185], v235, s[6:7] offset:528
	s_waitcnt vmcnt(16)
	v_lshlrev_b32_e32 v140, 16, v198
	v_and_b32_e32 v141, 0xffff0000, v198
	v_lshlrev_b32_e32 v142, 16, v199
	v_and_b32_e32 v143, 0xffff0000, v199
	v_lshlrev_b32_e32 v144, 16, v200
	v_and_b32_e32 v145, 0xffff0000, v200
	v_lshlrev_b32_e32 v146, 16, v201
	v_and_b32_e32 v147, 0xffff0000, v201
	v_pk_fma_f32 v[70:71], v[70:71], v[140:141], v[202:203]
	v_pk_fma_f32 v[72:73], v[72:73], v[142:143], v[204:205]
	v_pk_fma_f32 v[66:67], v[66:67], v[144:145], v[206:207]
	v_pk_fma_f32 v[68:69], v[68:69], v[146:147], v[208:209]
	v_cvt_pk_bf16_f32 v140, v70, v71
	v_cvt_pk_bf16_f32 v141, v72, v73
	v_cvt_pk_bf16_f32 v142, v66, v67
	v_cvt_pk_bf16_f32 v143, v68, v69
	global_store_dwordx4 v236, v[140:143], s[98:99] offset:256
	s_nop 1
	s_add_u32 s4, s4, 0x18000
	s_addc_u32 s5, s5, 0
	global_load_dwordx4 v[198:201], v234, s[4:5]
	s_add_u32 s6, s6, 0x10000
	s_addc_u32 s7, s7, 0
	global_load_dwordx4 v[202:205], v235, s[6:7]
	global_load_dwordx4 v[206:209], v235, s[6:7] offset:16
	s_waitcnt vmcnt(16)
	v_lshlrev_b32_e32 v140, 16, v210
	v_and_b32_e32 v141, 0xffff0000, v210
	v_lshlrev_b32_e32 v142, 16, v211
	v_and_b32_e32 v143, 0xffff0000, v211
	v_lshlrev_b32_e32 v144, 16, v212
	v_and_b32_e32 v145, 0xffff0000, v212
	v_lshlrev_b32_e32 v146, 16, v213
	v_and_b32_e32 v147, 0xffff0000, v213
	v_pk_fma_f32 v[62:63], v[62:63], v[140:141], v[214:215]
	v_pk_fma_f32 v[64:65], v[64:65], v[142:143], v[216:217]
	v_pk_fma_f32 v[58:59], v[58:59], v[144:145], v[218:219]
	v_pk_fma_f32 v[60:61], v[60:61], v[146:147], v[220:221]
	v_cvt_pk_bf16_f32 v140, v62, v63
	v_cvt_pk_bf16_f32 v141, v64, v65
	v_cvt_pk_bf16_f32 v142, v58, v59
	v_cvt_pk_bf16_f32 v143, v60, v61
	s_add_u32 s98, s98, 0x28000
	s_addc_u32 s99, s99, 0
	global_store_dwordx4 v236, v[140:143], s[98:99]
	s_nop 1
	global_load_dwordx4 v[210:213], v234, s[4:5] offset:256
	global_load_dwordx4 v[214:217], v235, s[6:7] offset:512
	global_load_dwordx4 v[218:221], v235, s[6:7] offset:528
	s_waitcnt vmcnt(16)
	v_lshlrev_b32_e32 v140, 16, v222
	v_and_b32_e32 v141, 0xffff0000, v222
	v_lshlrev_b32_e32 v142, 16, v223
	v_and_b32_e32 v143, 0xffff0000, v223
	v_lshlrev_b32_e32 v144, 16, v224
	v_and_b32_e32 v145, 0xffff0000, v224
	v_lshlrev_b32_e32 v146, 16, v225
	v_and_b32_e32 v147, 0xffff0000, v225
	v_pk_fma_f32 v[54:55], v[54:55], v[140:141], v[226:227]
	v_pk_fma_f32 v[56:57], v[56:57], v[142:143], v[228:229]
	v_pk_fma_f32 v[50:51], v[50:51], v[144:145], v[230:231]
	v_pk_fma_f32 v[52:53], v[52:53], v[146:147], v[232:233]
	v_cvt_pk_bf16_f32 v140, v54, v55
	v_cvt_pk_bf16_f32 v141, v56, v57
	v_cvt_pk_bf16_f32 v142, v50, v51
	v_cvt_pk_bf16_f32 v143, v52, v53
	global_store_dwordx4 v236, v[140:143], s[98:99] offset:256
	s_nop 1
	s_add_u32 s4, s4, 0x18000
	s_addc_u32 s5, s5, 0
	global_load_dwordx4 v[222:225], v234, s[4:5]
	s_add_u32 s6, s6, 0x10000
	s_addc_u32 s7, s7, 0
	global_load_dwordx4 v[226:229], v235, s[6:7]
	global_load_dwordx4 v[230:233], v235, s[6:7] offset:16
	s_waitcnt vmcnt(16)
; __device__ __forceinline__ u32x4 pack8(f32x4 v0, f32x4 v1) { u32x4 o; o.x = pkbf(v0.x, v0.y); o.y = pkbf(v0.z, v0.w); o.z = pkbf(v1.x, v1.y); o.w = pkbf(v1.z, v1.w); return o; }
;     __device__ __forceinline__ void operator()(int row, int col, f32x4 v0, f32x4 v1) const { *(u32x4*)(G + (size_t)row * 1024 + col) = pack8(v0, v1); }
;     __device__ __forceinline__ void operator()(const pg8::f32x4 (&acc)[2][2][4][2], const pg8::Unit& u, int wr, int wc, int fr, int fq) const {
;         const int row0 = u.pm * 256 + wr * 64 + fr, col0 = u.pn * 256 + wc * 32 + 8 * fq;
; #pragma unroll
;         for (int ai = 0; ai < 2; ++ai)
; #pragma unroll
;             for (int m = 0; m < 4; ++m)
; #pragma unroll
;                 for (int bj = 0; bj < 2; ++bj) { op(row0 + ai * 128 + m * 16, col0 + bj * 128, acc[ai][bj][m][0], acc[ai][bj][m][1]); asm volatile("" ::: "memory"); }
;     }
;     __device__ __forceinline__ void operator()(int row, int col, f32x4 v0, f32x4 v1) const {
;         f32x4 g0, g1; unpack8(*(const u32x4*)(GT + (size_t)row * 3072 + KB * 1024 + col), g0, g1);
;         float* mf = MF + (size_t)row * 1024 + col;
;         f32x4 r0 = g0 * v0, r1 = g1 * v1;
;         if (KB > 0) { r0 += *(const f32x4*)mf; r1 += *(const f32x4*)(mf + 4); }
;         if (KB < 2) { *(f32x4*)mf = r0; *(f32x4*)(mf + 4) = r1; }
;         else *(u32x4*)(MB + (size_t)row * 1024 + col) = pack8(r0, r1);
;     }
	v_lshlrev_b32_e32 v140, 16, v156
	v_and_b32_e32 v141, 0xffff0000, v156
	v_lshlrev_b32_e32 v142, 16, v157
	v_and_b32_e32 v143, 0xffff0000, v157
	v_lshlrev_b32_e32 v144, 16, v158
	v_and_b32_e32 v145, 0xffff0000, v158
	v_lshlrev_b32_e32 v146, 16, v159
	v_and_b32_e32 v147, 0xffff0000, v159
	v_pk_fma_f32 v[46:47], v[46:47], v[140:141], v[160:161]
	v_pk_fma_f32 v[48:49], v[48:49], v[142:143], v[162:163]
	v_pk_fma_f32 v[42:43], v[42:43], v[144:145], v[164:165]
	v_pk_fma_f32 v[44:45], v[44:45], v[146:147], v[166:167]
	v_cvt_pk_bf16_f32 v140, v46, v47
	v_cvt_pk_bf16_f32 v141, v48, v49
	v_cvt_pk_bf16_f32 v142, v42, v43
	v_cvt_pk_bf16_f32 v143, v44, v45
	s_add_u32 s98, s98, 0x8000
	s_addc_u32 s99, s99, 0
	global_store_dwordx4 v236, v[140:143], s[98:99]
	s_nop 1
	global_load_dwordx4 v[156:159], v234, s[4:5] offset:256
	global_load_dwordx4 v[160:163], v235, s[6:7] offset:512
	global_load_dwordx4 v[164:167], v235, s[6:7] offset:528
	s_waitcnt vmcnt(16)
	v_lshlrev_b32_e32 v140, 16, v168
	v_and_b32_e32 v141, 0xffff0000, v168
	v_lshlrev_b32_e32 v142, 16, v169
	v_and_b32_e32 v143, 0xffff0000, v169
	v_lshlrev_b32_e32 v144, 16, v170
	v_and_b32_e32 v145, 0xffff0000, v170
	v_lshlrev_b32_e32 v146, 16, v171
	v_and_b32_e32 v147, 0xffff0000, v171
	v_pk_fma_f32 v[38:39], v[38:39], v[140:141], v[174:175]
	v_pk_fma_f32 v[40:41], v[40:41], v[142:143], v[176:177]
	v_pk_fma_f32 v[34:35], v[34:35], v[144:145], v[182:183]
	v_pk_fma_f32 v[36:37], v[36:37], v[146:147], v[184:185]
	v_cvt_pk_bf16_f32 v140, v38, v39
	v_cvt_pk_bf16_f32 v141, v40, v41
	v_cvt_pk_bf16_f32 v142, v34, v35
	v_cvt_pk_bf16_f32 v143, v36, v37
	global_store_dwordx4 v236, v[140:143], s[98:99] offset:256
	s_nop 1
	s_waitcnt vmcnt(13)
	v_lshlrev_b32_e32 v140, 16, v198
	v_and_b32_e32 v141, 0xffff0000, v198
	v_lshlrev_b32_e32 v142, 16, v199
	v_and_b32_e32 v143, 0xffff0000, v199
	v_lshlrev_b32_e32 v144, 16, v200
	v_and_b32_e32 v145, 0xffff0000, v200
	v_lshlrev_b32_e32 v146, 16, v201
	v_and_b32_e32 v147, 0xffff0000, v201
	v_pk_fma_f32 v[30:31], v[30:31], v[140:141], v[202:203]
	v_pk_fma_f32 v[32:33], v[32:33], v[142:143], v[204:205]
	v_pk_fma_f32 v[26:27], v[26:27], v[144:145], v[206:207]
	v_pk_fma_f32 v[28:29], v[28:29], v[146:147], v[208:209]
	v_cvt_pk_bf16_f32 v140, v30, v31
	v_cvt_pk_bf16_f32 v141, v32, v33
	v_cvt_pk_bf16_f32 v142, v26, v27
	v_cvt_pk_bf16_f32 v143, v28, v29
	s_add_u32 s98, s98, 0x8000
	s_addc_u32 s99, s99, 0
	global_store_dwordx4 v236, v[140:143], s[98:99]
	s_nop 1
	s_waitcnt vmcnt(10)
	v_lshlrev_b32_e32 v140, 16, v210
	v_and_b32_e32 v141, 0xffff0000, v210
	v_lshlrev_b32_e32 v142, 16, v211
	v_and_b32_e32 v143, 0xffff0000, v211
	v_lshlrev_b32_e32 v144, 16, v212
	v_and_b32_e32 v145, 0xffff0000, v212
	v_lshlrev_b32_e32 v146, 16, v213
	v_and_b32_e32 v147, 0xffff0000, v213
	v_pk_fma_f32 v[22:23], v[22:23], v[140:141], v[214:215]
	v_pk_fma_f32 v[24:25], v[24:25], v[142:143], v[216:217]
	v_pk_fma_f32 v[18:19], v[18:19], v[144:145], v[218:219]
	v_pk_fma_f32 v[20:21], v[20:21], v[146:147], v[220:221]
	v_cvt_pk_bf16_f32 v140, v22, v23
	v_cvt_pk_bf16_f32 v141, v24, v25
	v_cvt_pk_bf16_f32 v142, v18, v19
	v_cvt_pk_bf16_f32 v143, v20, v21
	global_store_dwordx4 v236, v[140:143], s[98:99] offset:256
	s_nop 1
	s_waitcnt vmcnt(7)
	v_lshlrev_b32_e32 v140, 16, v222
	v_and_b32_e32 v141, 0xffff0000, v222
	v_lshlrev_b32_e32 v142, 16, v223
	v_and_b32_e32 v143, 0xffff0000, v223
	v_lshlrev_b32_e32 v144, 16, v224
	v_and_b32_e32 v145, 0xffff0000, v224
	v_lshlrev_b32_e32 v146, 16, v225
	v_and_b32_e32 v147, 0xffff0000, v225
	v_pk_fma_f32 v[14:15], v[14:15], v[140:141], v[226:227]
	v_pk_fma_f32 v[16:17], v[16:17], v[142:143], v[228:229]
	v_pk_fma_f32 v[10:11], v[10:11], v[144:145], v[230:231]
	v_pk_fma_f32 v[12:13], v[12:13], v[146:147], v[232:233]
	v_cvt_pk_bf16_f32 v140, v14, v15
	v_cvt_pk_bf16_f32 v141, v16, v17
	v_cvt_pk_bf16_f32 v142, v10, v11
	v_cvt_pk_bf16_f32 v143, v12, v13
	s_add_u32 s98, s98, 0x8000
	s_addc_u32 s99, s99, 0
	global_store_dwordx4 v236, v[140:143], s[98:99]
	s_nop 1
	s_waitcnt vmcnt(4)
	v_lshlrev_b32_e32 v140, 16, v156
	v_and_b32_e32 v141, 0xffff0000, v156
	v_lshlrev_b32_e32 v142, 16, v157
	v_and_b32_e32 v143, 0xffff0000, v157
	v_lshlrev_b32_e32 v144, 16, v158
	v_and_b32_e32 v145, 0xffff0000, v158
	v_lshlrev_b32_e32 v146, 16, v159
	v_and_b32_e32 v147, 0xffff0000, v159
	v_pk_fma_f32 v[6:7], v[6:7], v[140:141], v[160:161]
	v_pk_fma_f32 v[8:9], v[8:9], v[142:143], v[162:163]
	v_pk_fma_f32 v[2:3], v[2:3], v[144:145], v[164:165]
	v_pk_fma_f32 v[4:5], v[4:5], v[146:147], v[166:167]
	v_cvt_pk_bf16_f32 v140, v6, v7
	v_cvt_pk_bf16_f32 v141, v8, v9
	v_cvt_pk_bf16_f32 v142, v2, v3
	v_cvt_pk_bf16_f32 v143, v4, v5
	global_store_dwordx4 v236, v[140:143], s[98:99] offset:256
	s_nop 1
	s_and_b64 vcc, exec, s[40:41]
	s_mov_b64 s[4:5], -1
	s_cbranch_vccnz .LBB0_210
	s_andn2_b64 vcc, exec, s[54:55]
	s_cbranch_vccnz .LBB0_209
	s_barrier
	s_branch .LBB0_209
